# cache policy: f32 weight conversion loads (P0, P3) and the late-use FFN2 weight stores of P3 also non-temporal
# baseline (speedup 1.0000x reference)
.LBB0_77:
	s_or_saveexec_b64 s[12:13], s[4:5]
	s_mul_i32 s4, s41, s44
	s_add_i32 s84, s39, s4
	v_lshl_add_u64 v[16:17], v[12:13], 2, s[80:81]
	v_mov_b32_e32 v5, 0
	v_add_u32_e32 v18, s84, v10
	v_cmp_ne_u32_e64 s[4:5], 1, v33
	v_mov_b32_e32 v4, 0
	v_mov_b32_e32 v3, 0
	v_mov_b32_e32 v2, 0
	s_xor_b64 exec, exec, s[12:13]
	s_cbranch_execz .LBB0_82
	v_ashrrev_i32_e32 v19, 31, v18
	v_mul_lo_u32 v4, s82, v19
	v_mul_lo_u32 v5, s83, v18
	v_mad_u64_u32 v[2:3], s[44:45], s82, v18, 0
	v_add3_u32 v3, v3, v4, v5
	v_lshl_add_u64 v[2:3], v[2:3], 2, v[16:17]
	global_load_dwordx4 v[6:9], v[2:3], off nt
	s_and_b64 vcc, exec, s[4:5]
	s_cbranch_vccnz .LBB0_80
	v_lshl_add_u64 v[2:3], v[18:19], 2, s[34:35]
	global_load_dword v2, v[2:3], off
	s_waitcnt vmcnt(0)
	v_pk_mul_f32 v[6:7], v[6:7], v[2:3] op_sel_hi:[1,0]
	v_pk_mul_f32 v[8:9], v[8:9], v[2:3] op_sel_hi:[1,0]
.LBB0_80:
	v_add_u32_e32 v2, 16, v18
	v_ashrrev_i32_e32 v3, 31, v2
	v_mul_lo_u32 v4, s82, v3
	v_mul_lo_u32 v5, s83, v2
	v_mad_u64_u32 v[2:3], s[44:45], s82, v2, 0
	v_add3_u32 v3, v3, v4, v5
	v_lshl_add_u64 v[2:3], v[2:3], 2, v[16:17]
	global_load_dwordx4 v[2:5], v[2:3], off nt
	s_and_b64 vcc, exec, s[4:5]
	s_waitcnt vmcnt(1)
	ds_write2_b32 v28, v6, v7 offset1:1
	ds_write2_b32 v28, v8, v9 offset0:2 offset1:3
	s_cbranch_vccnz .LBB0_82
	s_ashr_i32 s85, s84, 31
	v_lshl_add_u64 v[6:7], s[84:85], 0, v[10:11]
	v_lshl_add_u64 v[6:7], v[6:7], 2, s[34:35]
	global_load_dword v6, v[6:7], off offset:64
	s_waitcnt vmcnt(0)
	v_pk_mul_f32 v[2:3], v[2:3], v[6:7] op_sel_hi:[1,0]
	v_pk_mul_f32 v[4:5], v[4:5], v[6:7] op_sel_hi:[1,0]

.LBB0_84:
	s_or_saveexec_b64 s[6:7], s[6:7]
	v_mov_b32_e32 v5, 0
	v_mov_b32_e32 v4, 0
	v_mov_b32_e32 v3, 0
	v_mov_b32_e32 v2, 0
	s_xor_b64 exec, exec, s[6:7]
	s_cbranch_execz .LBB0_55
	v_add_u32_e32 v2, 32, v18
	v_ashrrev_i32_e32 v3, 31, v2
	v_mul_lo_u32 v4, s82, v3
	v_mul_lo_u32 v5, s83, v2
	v_mad_u64_u32 v[2:3], s[12:13], s82, v2, 0
	v_add3_u32 v3, v3, v4, v5
	v_lshl_add_u64 v[2:3], v[2:3], 2, v[16:17]
	global_load_dwordx4 v[6:9], v[2:3], off nt
	s_and_b64 vcc, exec, s[4:5]
	s_cbranch_vccnz .LBB0_87
	s_ashr_i32 s85, s84, 31
	v_lshl_add_u64 v[2:3], s[84:85], 0, v[10:11]
	v_lshl_add_u64 v[2:3], v[2:3], 2, s[34:35]
	global_load_dword v2, v[2:3], off offset:128
	s_waitcnt vmcnt(0)
	v_pk_mul_f32 v[6:7], v[6:7], v[2:3] op_sel_hi:[1,0]
	v_pk_mul_f32 v[8:9], v[8:9], v[2:3] op_sel_hi:[1,0]
.LBB0_87:
	v_add_u32_e32 v2, 48, v18
	v_ashrrev_i32_e32 v3, 31, v2
	v_mul_lo_u32 v4, s82, v3
	v_mul_lo_u32 v5, s83, v2
	v_mad_u64_u32 v[2:3], s[12:13], s82, v2, 0
	v_add3_u32 v3, v3, v4, v5
	v_lshl_add_u64 v[2:3], v[2:3], 2, v[16:17]
	global_load_dwordx4 v[2:5], v[2:3], off nt
	s_and_b64 vcc, exec, s[4:5]
	s_waitcnt vmcnt(1)
	ds_write2_b32 v30, v6, v7 offset1:1
	ds_write2_b32 v30, v8, v9 offset0:2 offset1:3
	s_cbranch_vccnz .LBB0_55
	s_ashr_i32 s85, s84, 31
	v_lshl_add_u64 v[6:7], s[84:85], 0, v[10:11]
	v_lshl_add_u64 v[6:7], v[6:7], 2, s[34:35]
	global_load_dword v6, v[6:7], off offset:192
	s_waitcnt vmcnt(0)
	v_pk_mul_f32 v[2:3], v[2:3], v[6:7] op_sel_hi:[1,0]
	v_pk_mul_f32 v[4:5], v[4:5], v[6:7] op_sel_hi:[1,0]
	s_branch .LBB0_55

.LBB0_116:
	s_or_b64 exec, exec, s[0:1]
	v_lshl_add_u64 v[16:17], v[16:17], 0, v[10:11]
	global_load_dwordx4 v[26:29], v[16:17], off nt
	global_load_dwordx4 v[30:33], v[16:17], off offset:1024 nt
	global_load_dwordx4 v[34:37], v[16:17], off offset:2048 nt
	global_load_dwordx4 v[38:41], v[16:17], off offset:3072 nt
	v_lshl_add_u64 v[12:13], v[12:13], 0, s[6:7]
	v_lshlrev_b64 v[14:15], 11, v[14:15]
	v_cmp_lt_i32_e64 s[0:1], s14, v12
	v_lshl_add_u64 v[14:15], v[6:7], 0, v[14:15]
	s_or_b64 s[8:9], s[0:1], s[8:9]
	v_lshl_add_u64 v[8:9], v[8:9], 0, s[16:17]
	s_waitcnt vmcnt(3)
	v_mov_b32_e32 v42, v27
	s_waitcnt vmcnt(2)
	v_mov_b32_e32 v43, v31
	v_mov_b32_e32 v16, v26
	v_mov_b32_e32 v17, v30
	s_waitcnt vmcnt(1)
	v_mov_b32_e32 v50, v35
	s_waitcnt vmcnt(0)
	v_mov_b32_e32 v51, v39
	v_pk_mul_f32 v[42:43], v[42:43], v[42:43]
	v_mov_b32_e32 v44, v28
	v_mov_b32_e32 v45, v32
	v_mov_b32_e32 v48, v34
	v_mov_b32_e32 v49, v38
	v_pk_mul_f32 v[50:51], v[50:51], v[50:51]
	v_pk_fma_f32 v[16:17], v[16:17], v[16:17], v[42:43]
	v_mov_b32_e32 v46, v29
	v_mov_b32_e32 v47, v33
	v_mov_b32_e32 v52, v36
	v_mov_b32_e32 v53, v40
	v_pk_fma_f32 v[42:43], v[48:49], v[48:49], v[50:51]
	v_pk_fma_f32 v[16:17], v[44:45], v[44:45], v[16:17]
	v_mov_b32_e32 v54, v37
	v_mov_b32_e32 v55, v41
	v_pk_fma_f32 v[42:43], v[52:53], v[52:53], v[42:43]
	v_pk_fma_f32 v[16:17], v[46:47], v[46:47], v[16:17]
	v_pk_fma_f32 v[42:43], v[54:55], v[54:55], v[42:43]
	v_add_f32_e32 v4, v16, v17
	v_add_f32_e32 v4, v4, v42
	v_add_f32_e32 v4, v4, v43
	ds_bpermute_b32 v16, v3, v4
	s_waitcnt lgkmcnt(0)
	v_add_f32_e32 v4, v4, v16
	ds_bpermute_b32 v16, v20, v4
	s_waitcnt lgkmcnt(0)
	v_add_f32_e32 v4, v4, v16
	ds_bpermute_b32 v16, v21, v4
	s_waitcnt lgkmcnt(0)
	v_add_f32_e32 v4, v4, v16
	ds_bpermute_b32 v16, v22, v4
	s_waitcnt lgkmcnt(0)
	v_add_f32_e32 v4, v4, v16
	ds_bpermute_b32 v16, v23, v4
	s_waitcnt lgkmcnt(0)
	v_add_f32_e32 v4, v4, v16
	ds_bpermute_b32 v16, v24, v4
	s_waitcnt lgkmcnt(0)
	v_add_f32_e32 v4, v4, v16
	v_fmamk_f32 v4, v4, 0x3a800000, v25
	v_mul_f32_e32 v16, 0x4b800000, v4
	v_cmp_gt_f32_e32 vcc, s13, v4
	s_nop 1
	v_cndmask_b32_e32 v4, v4, v16, vcc
	v_rsq_f32_e32 v4, v4
	s_nop 0
	v_mul_f32_e32 v16, 0x45800000, v4
	v_cndmask_b32_e32 v4, v4, v16, vcc
	v_pk_mul_f32 v[16:17], v[4:5], v[28:29] op_sel_hi:[0,1]
	v_pk_mul_f32 v[26:27], v[4:5], v[26:27] op_sel_hi:[0,1]
	v_pk_mul_f32 v[28:29], v[4:5], v[32:33] op_sel_hi:[0,1]
	v_pk_mul_f32 v[30:31], v[4:5], v[30:31] op_sel_hi:[0,1]
	v_pk_mul_f32 v[32:33], v[4:5], v[36:37] op_sel_hi:[0,1]
	v_pk_mul_f32 v[34:35], v[4:5], v[34:35] op_sel_hi:[0,1]
	v_pk_mul_f32 v[36:37], v[4:5], v[40:41] op_sel_hi:[0,1]
	v_pk_mul_f32 v[38:39], v[4:5], v[38:39] op_sel_hi:[0,1]
	v_cvt_pk_bf16_f32 v26, v26, v27
	v_cvt_pk_bf16_f32 v27, v16, v17
	v_cvt_pk_bf16_f32 v16, v30, v31
	v_cvt_pk_bf16_f32 v17, v28, v29
	v_cvt_pk_bf16_f32 v28, v34, v35
	v_cvt_pk_bf16_f32 v29, v32, v33
	v_cvt_pk_bf16_f32 v30, v38, v39
	v_cvt_pk_bf16_f32 v31, v36, v37
	global_store_dwordx2 v[14:15], v[26:27], off
	global_store_dwordx2 v[14:15], v[16:17], off offset:512
	global_store_dwordx2 v[14:15], v[28:29], off offset:1024
	global_store_dwordx2 v[14:15], v[30:31], off offset:1536
	s_andn2_b64 exec, exec, s[8:9]
	s_cbranch_execz .LBB0_119

.LBB0_354:
	s_or_b64 exec, exec, s[8:9]
	s_waitcnt vmcnt(0)
	ds_write2_b32 v28, v2, v3 offset1:1
	ds_write2_b32 v28, v4, v5 offset0:2 offset1:3
	s_waitcnt lgkmcnt(0)
	s_barrier
	ds_read2_b32 v[6:7], v24 offset1:32
	ds_read2_b32 v[8:9], v24 offset0:65 offset1:97
	ds_read2_b32 v[16:17], v24 offset0:130 offset1:162
	ds_read2_b32 v[18:19], v24 offset0:195 offset1:227
	v_add_u32_e32 v2, 0x400, v24
	ds_read2_b32 v[32:33], v2 offset0:4 offset1:36
	ds_read2_b32 v[34:35], v2 offset0:69 offset1:101
	ds_read2_b32 v[36:37], v2 offset0:134 offset1:166
	ds_read2_b32 v[38:39], v2 offset0:199 offset1:231
	s_waitcnt lgkmcnt(6)
	v_cvt_pk_bf16_f32 v2, v6, v8
	v_or_b32_e32 v6, s49, v23
	s_ashr_i32 s43, s42, 31
	v_mad_i64_i32 v[40:41], s[6:7], s40, v6, 0
	v_lshl_add_u64 v[40:41], v[40:41], 1, s[38:39]
	s_lshl_b64 s[6:7], s[42:43], 1
	v_lshl_add_u64 v[40:41], v[40:41], 0, s[6:7]
	v_mov_b32_e32 v15, v13
	s_waitcnt lgkmcnt(4)
	v_cvt_pk_bf16_f32 v3, v16, v18
	s_waitcnt lgkmcnt(2)
	v_cvt_pk_bf16_f32 v4, v32, v34
	s_waitcnt lgkmcnt(0)
	v_cvt_pk_bf16_f32 v5, v36, v38
	v_lshl_add_u64 v[40:41], v[40:41], 0, v[14:15]
	v_or_b32_e32 v6, s49, v29
	global_store_dwordx4 v[40:41], v[2:5], off nt
	s_add_i32 s44, s44, s3
	s_add_i32 s45, s45, s48
	v_cvt_pk_bf16_f32 v2, v7, v9
	v_mad_i64_i32 v[6:7], s[8:9], s40, v6, 0
	v_lshl_add_u64 v[6:7], v[6:7], 1, s[38:39]
	v_lshl_add_u64 v[6:7], v[6:7], 0, s[6:7]
	v_cvt_pk_bf16_f32 v3, v17, v19
	v_cvt_pk_bf16_f32 v4, v33, v35
	v_cvt_pk_bf16_f32 v5, v37, v39
	v_lshl_add_u64 v[6:7], v[6:7], 0, v[14:15]
	s_cmp_lt_i32 s44, s37
	global_store_dwordx4 v[6:7], v[2:5], off nt
	s_barrier
	s_cbranch_scc0 .LBB0_342

.LBB0_359:
	s_or_saveexec_b64 s[12:13], s[6:7]
	s_mul_i32 s6, s46, s42
	s_add_i32 s42, s45, s6
	v_lshl_add_u64 v[16:17], v[12:13], 2, s[34:35]
	v_mov_b32_e32 v5, 0
	v_add_u32_e32 v18, s42, v10
	v_cmp_ne_u32_e64 s[6:7], 1, v30
	v_mov_b32_e32 v4, 0
	v_mov_b32_e32 v3, 0
	v_mov_b32_e32 v2, 0
	s_xor_b64 exec, exec, s[12:13]
	s_cbranch_execz .LBB0_364
	v_mad_i64_i32 v[2:3], s[50:51], s36, v18, 0
	v_lshl_add_u64 v[2:3], v[2:3], 2, v[16:17]
	global_load_dwordx4 v[6:9], v[2:3], off nt
	s_and_b64 vcc, exec, s[6:7]
	v_ashrrev_i32_e32 v19, 31, v18
	s_cbranch_vccnz .LBB0_362
	v_lshl_add_u64 v[2:3], v[18:19], 2, s[10:11]
	global_load_dword v2, v[2:3], off
	s_waitcnt vmcnt(0)
	v_pk_mul_f32 v[6:7], v[6:7], v[2:3] op_sel_hi:[1,0]
	v_pk_mul_f32 v[8:9], v[8:9], v[2:3] op_sel_hi:[1,0]
.LBB0_362:
	v_add_u32_e32 v2, 16, v18
	v_mad_i64_i32 v[2:3], s[50:51], s36, v2, 0
	v_lshl_add_u64 v[2:3], v[2:3], 2, v[16:17]
	global_load_dwordx4 v[2:5], v[2:3], off nt
	s_and_b64 vcc, exec, s[6:7]
	s_waitcnt vmcnt(1)
	ds_write2_b32 v25, v6, v7 offset1:1
	ds_write2_b32 v25, v8, v9 offset0:2 offset1:3
	s_cbranch_vccnz .LBB0_364
	s_ashr_i32 s43, s42, 31
	v_lshl_add_u64 v[6:7], s[42:43], 0, v[10:11]
	v_lshl_add_u64 v[6:7], v[6:7], 2, s[10:11]
	global_load_dword v6, v[6:7], off offset:64
	s_waitcnt vmcnt(0)
	v_pk_mul_f32 v[2:3], v[2:3], v[6:7] op_sel_hi:[1,0]
	v_pk_mul_f32 v[4:5], v[4:5], v[6:7] op_sel_hi:[1,0]

.LBB0_366:
	s_or_saveexec_b64 s[8:9], s[8:9]
	v_mov_b32_e32 v5, 0
	v_mov_b32_e32 v4, 0
	v_mov_b32_e32 v3, 0
	v_mov_b32_e32 v2, 0
	s_xor_b64 exec, exec, s[8:9]
	s_cbranch_execz .LBB0_354
	v_add_u32_e32 v2, 32, v18
	v_mad_i64_i32 v[2:3], s[12:13], s36, v2, 0
	v_lshl_add_u64 v[2:3], v[2:3], 2, v[16:17]
	global_load_dwordx4 v[6:9], v[2:3], off nt
	s_and_b64 vcc, exec, s[6:7]
	s_cbranch_vccnz .LBB0_369
	s_ashr_i32 s43, s42, 31
	v_lshl_add_u64 v[2:3], s[42:43], 0, v[10:11]
	v_lshl_add_u64 v[2:3], v[2:3], 2, s[10:11]
	global_load_dword v2, v[2:3], off offset:128
	s_waitcnt vmcnt(0)
	v_pk_mul_f32 v[6:7], v[6:7], v[2:3] op_sel_hi:[1,0]
	v_pk_mul_f32 v[8:9], v[8:9], v[2:3] op_sel_hi:[1,0]
.LBB0_369:
	v_add_u32_e32 v2, 48, v18
	v_mad_i64_i32 v[2:3], s[12:13], s36, v2, 0
	v_lshl_add_u64 v[2:3], v[2:3], 2, v[16:17]
	global_load_dwordx4 v[2:5], v[2:3], off nt
	s_and_b64 vcc, exec, s[6:7]
	s_waitcnt vmcnt(1)
	ds_write2_b32 v27, v6, v7 offset1:1
	ds_write2_b32 v27, v8, v9 offset0:2 offset1:3
	s_cbranch_vccnz .LBB0_354
	s_ashr_i32 s43, s42, 31
	v_lshl_add_u64 v[6:7], s[42:43], 0, v[10:11]
	v_lshl_add_u64 v[6:7], v[6:7], 2, s[10:11]
	global_load_dword v6, v[6:7], off offset:192
	s_waitcnt vmcnt(0)
	v_pk_mul_f32 v[2:3], v[2:3], v[6:7] op_sel_hi:[1,0]
	v_pk_mul_f32 v[4:5], v[4:5], v[6:7] op_sel_hi:[1,0]
	s_branch .LBB0_354
